# v17 = v16 + packed row-sum adds on the attention slow-path / split-loop pre-barrier tails split into scalar pairs
# baseline (speedup 1.0000x reference)
; DI unsigned pk_bf16(float lo, float hi) { f32x2 v = {lo, hi}; bf16v2 b = __builtin_convertvector(v, bf16v2); return __builtin_bit_cast(unsigned, b); }
; DI void attn_item(const Params& p, int g, int seq, int hd, int qt, int m, char* smem, int split_j, int sub) {
;     ...
;     for (int s2 = 0; s2 < 2; ++s2) {
;       u32x4 w; w.x = pk_bf16(X[8 * s2], X[8 * s2 + 1]); w.y = pk_bf16(X[8 * s2 + 2], X[8 * s2 + 3]); w.z = pk_bf16(X[8 * s2 + 4], X[8 * s2 + 5]); w.w = pk_bf16(X[8 * s2 + 6], X[8 * s2 + 7]);
;       ls2 += (f32x2){X[8 * s2], X[8 * s2 + 1]}; ls2 += (f32x2){X[8 * s2 + 2], X[8 * s2 + 3]};
;       ls2 += (f32x2){X[8 * s2 + 4], X[8 * s2 + 5]}; ls2 += (f32x2){X[8 * s2 + 6], X[8 * s2 + 7]};
;       pf[s2] = __builtin_bit_cast(bf16x8, w);
;     ...
;   for (int it = 0; it < npairs; ++it) {
;     const int set = it & 1;
;     if (it + 1 < npairs) { load_tile(2 * it + 2, rkA, rvA0, rvA1); load_tile(2 * it + 3, rkB, rvB0, rvB1); }
.LBB0_265:
	v_add_f32_e32 v64, v186, v64
	v_add_f32_e32 v65, v187, v65
	s_add_i32 s11, s11, 2
	v_add_f32_e32 v64, v66, v64
	v_add_f32_e32 v65, v67, v65
	s_add_i32 s14, s14, 64
	v_add_f32_e32 v64, v68, v64
	v_add_f32_e32 v65, v69, v65
	v_add_u32_e32 v198, 64, v198
	v_add_f32_e32 v64, v70, v64
	v_add_f32_e32 v65, v71, v65
	v_add_f32_e32 v64, v72, v64
	v_add_f32_e32 v65, v73, v65
	v_add_f32_e32 v64, v74, v64
	v_add_f32_e32 v65, v75, v65
	v_add_f32_e32 v64, v76, v64
	v_add_f32_e32 v65, v77, v65
	s_nop 0
	v_add_f32_e32 v186, v78, v64
	v_add_f32_e32 v187, v79, v65
	s_cmp_lg_u32 s77, s15
	s_cbranch_scc0 .Lar_exit
	s_add_i32 s15, s15, 1
	s_cmp_lt_u32 s15, s77
	s_cselect_b64 s[6:7], -1, 0
	s_cmp_ge_u32 s15, s77
	s_cbranch_scc1 .Lar_t
	s_add_i32 s17, s10, s11
	s_add_i32 s50, s17, 2
	s_lshl_b64 s[8:9], s[50:51], 12
	v_lshl_add_u64 v[236:237], v[178:179], 0, s[8:9]
	s_lshl_b64 s[8:9], s[50:51], 13
	v_lshl_add_u64 v[238:239], v[176:177], 0, s[8:9]
	s_add_i32 s50, s17, 3
	global_load_dwordx4 v[96:99], v[236:237], off
	global_load_dwordx4 v[100:103], v[238:239], off
	v_add_co_u32_e32 v236, vcc, 0x1000, v238
	s_lshl_b64 s[8:9], s[50:51], 12
	s_nop 0
	v_addc_co_u32_e32 v237, vcc, 0, v239, vcc
	v_lshl_add_u64 v[238:239], v[178:179], 0, s[8:9]
	s_lshl_b64 s[8:9], s[50:51], 13
	global_load_dwordx4 v[120:123], v[236:237], off
	global_load_dwordx4 v[124:127], v[238:239], off
	v_lshl_add_u64 v[236:237], v[176:177], 0, s[8:9]
	v_add_co_u32_e32 v238, vcc, 0x1000, v236
	s_nop 1
	v_addc_co_u32_e32 v239, vcc, 0, v237, vcc
	global_load_dwordx4 v[128:131], v[236:237], off
	global_load_dwordx4 v[132:135], v[238:239], off

; DI unsigned pk_bf16(float lo, float hi) { f32x2 v = {lo, hi}; bf16v2 b = __builtin_convertvector(v, bf16v2); return __builtin_bit_cast(unsigned, b); }
; DI void attn_item(const Params& p, int g, int seq, int hd, int qt, int m, char* smem, int split_j, int sub) {
;     ...
;     for (int s2 = 0; s2 < 2; ++s2) {
;       u32x4 w; w.x = pk_bf16(X[8 * s2], X[8 * s2 + 1]); w.y = pk_bf16(X[8 * s2 + 2], X[8 * s2 + 3]); w.z = pk_bf16(X[8 * s2 + 4], X[8 * s2 + 5]); w.w = pk_bf16(X[8 * s2 + 6], X[8 * s2 + 7]);
;       ls2 += (f32x2){X[8 * s2], X[8 * s2 + 1]}; ls2 += (f32x2){X[8 * s2 + 2], X[8 * s2 + 3]};
;       ls2 += (f32x2){X[8 * s2 + 4], X[8 * s2 + 5]}; ls2 += (f32x2){X[8 * s2 + 6], X[8 * s2 + 7]};
;       pf[s2] = __builtin_bit_cast(bf16x8, w);
;     ...
;   for (int it = 0; it < npairs; ++it) {
;     const int set = it & 1;
;     if (it + 1 < npairs) { load_tile(2 * it + 2, rkA, rvA0, rvA1); load_tile(2 * it + 3, rkB, rvB0, rvB1); }
;     compute(2 * it, 2 * set);
;     compute(2 * it + 1, 2 * set + 1);
;     if (it + 1 < npairs) { store_tile(2 * (set ^ 1), rkA, rvA0, rvA1); store_tile(2 * (set ^ 1) + 1, rkB, rvB0, rvB1); }
;     __syncthreads();
;   }
.LBB0_316:
	v_add_f32_e32 v64, v186, v64
	v_add_f32_e32 v65, v187, v65
	s_add_i32 s13, s13, 64
	v_add_f32_e32 v64, v66, v64
	v_add_f32_e32 v65, v67, v65
	s_add_i32 s6, s6, 2
	v_add_f32_e32 v64, v68, v64
	v_add_f32_e32 v65, v69, v65
	s_cmp_lg_u32 s73, s15
	v_add_f32_e32 v64, v70, v64
	v_add_f32_e32 v65, v71, v65
	s_waitcnt lgkmcnt(0)
	v_add_f32_e32 v64, v72, v64
	v_add_f32_e32 v65, v73, v65
	s_barrier
	v_add_f32_e32 v64, v74, v64
	v_add_f32_e32 v65, v75, v65
	s_nop 0
	v_add_f32_e32 v64, v76, v64
	v_add_f32_e32 v65, v77, v65
	s_nop 0
	v_add_f32_e32 v186, v78, v64
	v_add_f32_e32 v187, v79, v65
	s_cbranch_scc0 .LBB0_337
